# prologue w_in transpose: the 16 row-scale (norm_pre) loads of a tile issued together and waited once instead of 16 load+drain round trips
# baseline (speedup 1.0000x reference)
; #define LAS __attribute__((address_space(3)))
; __device__ void phase_ssd_out(KP P, int layer, LAS unsigned char* lds) {
;     ...
;     for (int item = blockIdx.x; item < 512; item += nblk) {
;         const int g = item & 1, bc = item >> 1, b = bc >> 6, c = bc & 63, tbase = c * 128, h = g * 8 + wid;
;         const long row0 = (long)b * SEQ + tbase;
;         const __amdgpu_buffer_rsrc_t rsq = seq_rsrc(proj, row0, tbase);
;         u32x4 rbc[4][4];
;         { const int cg16 = tid & 15, chbc = 1024 + ((cg16 >> 3) * 128) + g * 64 + (cg16 & 7) * 8;
; #pragma unroll
;           for (int i = 0; i < 4; ++i) conv8_load(rsq, tbase, (tid >> 4) + 32 * i, chbc, rbc[i]); }
;         { const f32x2* dcs = (const f32x2*)P->out; const f32x2 t0 = dcs[(row0 + 2 * lane) * 16 + h], t1 = dcs[(row0 + 2 * lane + 1) * 16 + h];
;           const float d0 = t0.x, cs0 = t0.y, d1 = t1.x, cs1 = t1.y;
;           csA[wid * 128 + 2 * lane] = cs0; csA[wid * 128 + 2 * lane + 1] = cs1; dtA[wid * 128 + 2 * lane] = d0; dtA[wid * 128 + 2 * lane + 1] = d1;
;           const float ce = __shfl(cs1, (lane & 48) | 15);
;           fsA[wid * 128 + 2 * lane] = __expf(ce - cs0); fsA[wid * 128 + 2 * lane + 1] = __expf(ce - cs1); }
;         {
;             float w[4][8], bias[8]; const int cgp = tid & 15, ch = 1024 + ((cgp >> 3) * 128) + g * 64 + (cgp & 7) * 8; load_conv_w(cw, cb, ch, w, bias);
;             LAS bf16_t* dstb = ((cgp >> 3) ? Cc : Bc) + (cgp & 7) * 8;
; #pragma unroll
;             for (int i = 0; i < 4; ++i) { const int l = (tid >> 4) + 32 * i; float o[8]; conv8_math(rbc[i], w, bias, o);
;                 *(LAS u32x4*)(dstb + l * 72) = __builtin_bit_cast(u32x4, pack8(o)); }
.LBB0_24:
	s_ashr_i32 s10, s22, 1
	s_lshl_b32 s13, s10, 7
	s_and_b32 s14, s13, 0x1f80
	s_and_b32 s11, s22, 1
	s_ashr_i32 s12, s22, 7
	v_add_u32_e32 v0, s14, v157
	s_ashr_i32 s13, s12, 31
	s_mul_i32 s20, s12, 0x4400000
	v_lshl_or_b32 v2, s11, 6, v198
	v_mul_lo_u32 v0, v0, s55
	s_mul_hi_i32 s15, s12, 0x4400000
	s_add_u32 s64, s3, s20
	v_or_b32_e32 v0, v0, v2
	s_load_dwordx2 s[24:25], s[36:37], 0x78
	s_addc_u32 s15, s16, s15
	v_lshlrev_b32_e32 v16, 1, v0
	s_lshl_b64 s[12:13], s[12:13], 13
	s_and_b32 s65, s15, 0xffff
	v_add_u32_e32 v0, 0xffffa200, v16
	s_or_b32 s12, s12, s14
	buffer_load_dwordx4 v[78:81], v0, s[64:67], 0 offen
	v_mov_b32_e32 v1, s13
	v_or_b32_e32 v0, s12, v152
	v_lshl_add_u32 v76, s11, 3, v153
	v_lshlrev_b64 v[0:1], 7, v[0:1]
	v_ashrrev_i32_e32 v77, 31, v76
	s_waitcnt lgkmcnt(0)
	v_lshl_add_u64 v[0:1], s[24:25], 0, v[0:1]
	v_lshl_add_u64 v[0:1], v[76:77], 3, v[0:1]
	global_load_dwordx2 v[106:107], v[0:1], off offset:128
	v_mov_b32_e32 v3, 0x1000
	v_lshl_or_b32 v168, v2, 2, v3
	global_load_dwordx4 v[4:7], v168, s[4:5]
	global_load_dwordx4 v[40:43], v168, s[6:7]
	global_load_dwordx2 v[108:109], v[0:1], off
	global_load_dwordx4 v[32:35], v168, s[4:5] offset:16
	global_load_dwordx4 v[36:39], v168, s[6:7] offset:16
	v_add_u32_e32 v0, 0xffffc400, v16
	v_add_u32_e32 v8, 0xffffe600, v16
	buffer_load_dwordx4 v[82:85], v0, s[64:67], 0 offen
	buffer_load_dwordx4 v[86:89], v8, s[64:67], 0 offen
	v_lshl_add_u64 v[0:1], s[4:5], 0, v[168:169]
	v_add_co_u32_e32 v2, vcc, s68, v0
	buffer_load_dwordx4 v[90:93], v16, s[64:67], 0 offen offset:2048
	s_nop 0
	v_addc_co_u32_e32 v3, vcc, 0, v1, vcc
	global_load_dwordx4 v[28:31], v[2:3], off offset:1024
	v_lshl_add_u64 v[2:3], v[0:1], 0, s[82:83]
	global_load_dwordx4 v[24:27], v[2:3], off offset:16
	v_add_co_u32_e32 v2, vcc, s69, v0
	v_add_u32_e32 v17, 0x3e000, v16
	s_nop 0
	v_addc_co_u32_e32 v3, vcc, 0, v1, vcc
	global_load_dwordx4 v[20:23], v[2:3], off offset:2048
	v_lshl_add_u64 v[2:3], v[0:1], 0, s[84:85]
	global_load_dwordx4 v[12:15], v[2:3], off offset:16
	v_add_co_u32_e32 v2, vcc, s70, v0
	v_add_u32_e32 v18, 0x40000, v16
	s_nop 0
	v_addc_co_u32_e32 v3, vcc, 0, v1, vcc
	global_load_dwordx4 v[8:11], v[2:3], off offset:3072
	v_lshl_add_u64 v[0:1], v[0:1], 0, s[86:87]
	global_load_dwordx4 v[0:3], v[0:1], off offset:16
	v_add_u32_e32 v19, 0x42000, v16
	v_add_u32_e32 v44, 0x44000, v16
	v_add_u32_e32 v45, 0x82000, v16
	v_add_u32_e32 v46, 0x84000, v16
	v_add_u32_e32 v47, 0x86000, v16
	v_add_u32_e32 v48, 0x88000, v16
	v_add_u32_e32 v49, 0xc6000, v16
	v_add_u32_e32 v50, 0xc8000, v16
	v_add_u32_e32 v110, 0xca000, v16
	v_add_u32_e32 v16, 0xcc000, v16
	buffer_load_dwordx4 v[94:97], v17, s[64:67], 0 offen offset:512
	buffer_load_dwordx4 v[98:101], v18, s[64:67], 0 offen offset:1024
	buffer_load_dwordx4 v[102:105], v19, s[64:67], 0 offen offset:1536
	buffer_load_dwordx4 v[72:75], v44, s[64:67], 0 offen offset:2048
	buffer_load_dwordx4 v[68:71], v45, s[64:67], 0 offen offset:512
	buffer_load_dwordx4 v[64:67], v46, s[64:67], 0 offen offset:1024
	buffer_load_dwordx4 v[60:63], v47, s[64:67], 0 offen offset:1536
	buffer_load_dwordx4 v[56:59], v48, s[64:67], 0 offen offset:2048
	buffer_load_dwordx4 v[52:55], v49, s[64:67], 0 offen offset:512
	s_nop 0
	buffer_load_dwordx4 v[48:51], v50, s[64:67], 0 offen offset:1024
	s_nop 0
	buffer_load_dwordx4 v[44:47], v110, s[64:67], 0 offen offset:1536
	s_nop 0
	buffer_load_dwordx4 v[16:19], v16, s[64:67], 0 offen offset:2048
	s_ashr_i32 s11, s10, 31
	s_lshl_b64 s[10:11], s[10:11], 17
	s_add_u32 s10, s17, s10
	s_addc_u32 s11, s18, s11
	v_lshlrev_b32_e32 v180, 6, v76
	v_ashrrev_i32_e32 v181, 31, v180
	v_mov_b32_e32 v161, v169
	v_mov_b32_e32 v163, v169
	v_mov_b32_e32 v165, v169
	s_mov_b32 s20, 0
	v_or_b32_e32 v175, v180, v190
	s_waitcnt vmcnt(27)
	v_lshlrev_b32_e32 v110, 16, v78
	v_and_b32_e32 v111, 0xffff0000, v78
	v_lshlrev_b32_e32 v78, 16, v79
	v_and_b32_e32 v79, 0xffff0000, v79
	s_waitcnt vmcnt(26)
	ds_bpermute_b32 v114, v171, v107
	s_waitcnt vmcnt(23)
	v_mov_b32_e32 v112, v109
	v_mov_b32_e32 v113, v107
	v_pk_fma_f32 v[78:79], v[6:7], v[78:79], v[42:43]
	v_pk_fma_f32 v[110:111], v[4:5], v[110:111], v[40:41]
	s_waitcnt lgkmcnt(0)
	v_sub_f32_e32 v109, v114, v109
	v_sub_f32_e32 v107, v114, v107
	v_mul_f32_e32 v109, 0x3fb8aa3b, v109
	v_mul_f32_e32 v107, 0x3fb8aa3b, v107
	v_exp_f32_e32 v114, v109
	v_exp_f32_e32 v115, v107
	v_mov_b32_e32 v109, v106
	ds_write2st64_b64 v159, v[112:113], v[108:109] offset0:72 offset1:80
	ds_write_b64 v188, v[114:115]
	v_lshlrev_b32_e32 v106, 16, v80
	v_and_b32_e32 v107, 0xffff0000, v80
	v_lshlrev_b32_e32 v80, 16, v81
	v_and_b32_e32 v81, 0xffff0000, v81
	s_waitcnt vmcnt(20)
	v_lshlrev_b32_e32 v108, 16, v82
	v_and_b32_e32 v109, 0xffff0000, v82
	v_lshlrev_b32_e32 v82, 16, v83
	v_and_b32_e32 v83, 0xffff0000, v83
	v_pk_fma_f32 v[80:81], v[34:35], v[80:81], v[38:39]
	s_waitcnt vmcnt(17)
	v_pk_fma_f32 v[78:79], v[30:31], v[82:83], v[78:79]
	v_lshlrev_b32_e32 v82, 16, v84
	v_and_b32_e32 v83, 0xffff0000, v84
	v_lshlrev_b32_e32 v84, 16, v85
	v_and_b32_e32 v85, 0xffff0000, v85
	v_pk_fma_f32 v[106:107], v[32:33], v[106:107], v[36:37]
	s_waitcnt vmcnt(16)
	v_pk_fma_f32 v[80:81], v[26:27], v[84:85], v[80:81]
	v_lshlrev_b32_e32 v84, 16, v86
	v_and_b32_e32 v85, 0xffff0000, v86
	v_lshlrev_b32_e32 v86, 16, v87
	v_and_b32_e32 v87, 0xffff0000, v87
	v_pk_fma_f32 v[82:83], v[24:25], v[82:83], v[106:107]
	s_waitcnt vmcnt(15)
	v_pk_fma_f32 v[78:79], v[22:23], v[86:87], v[78:79]
	v_lshlrev_b32_e32 v86, 16, v88
	v_and_b32_e32 v87, 0xffff0000, v88
	v_pk_fma_f32 v[108:109], v[28:29], v[108:109], v[110:111]
	s_waitcnt vmcnt(14)
; #define LAS __attribute__((address_space(3)))
; __device__ __forceinline__ float bflo(unsigned w) { return __uint_as_float(w << 16); }
; __device__ __forceinline__ float bfhi(unsigned w) { return __uint_as_float(w & 0xffff0000u); }
; __device__ __forceinline__ void conv8_math(const u32x4 (&raw)[4], const float (&w)[4][8], const float (&bias)[8], float (&o)[8]) {
;     f32x2 a[4];
; #pragma unroll
;     for (int j = 0; j < 4; ++j) a[j] = (f32x2){bias[2 * j], bias[2 * j + 1]};
; #pragma unroll
;     for (int k = 0; k < 4; ++k) {
; #pragma unroll
;         for (int j = 0; j < 4; ++j) { const unsigned u = raw[k][j]; const f32x2 v = (f32x2){bflo(u), bfhi(u)}, wv = (f32x2){w[k][2 * j], w[k][2 * j + 1]}; a[j] = wv * v + a[j]; } }
; #pragma unroll
;     for (int j = 0; j < 4; ++j) { float sa, sb; sigmoid2(a[j].x, a[j].y, sa, sb); o[2 * j] = a[j].x * sa; o[2 * j + 1] = a[j].y * sb; }
; __device__ void phase_ssd_out(KP P, int layer, LAS unsigned char* lds) {
;     ...
;             for (int i = 0; i < 4; ++i) { const int l = (tid >> 4) + 32 * i; float o[8]; conv8_math(rbc[i], w, bias, o);
;                 *(LAS u32x4*)(dstb + l * 72) = __builtin_bit_cast(u32x4, pack8(o)); }
	v_pk_fma_f32 v[82:83], v[12:13], v[86:87], v[82:83]
	v_lshlrev_b32_e32 v86, 16, v89
	v_and_b32_e32 v87, 0xffff0000, v89
	v_pk_fma_f32 v[84:85], v[20:21], v[84:85], v[108:109]
	v_pk_fma_f32 v[80:81], v[14:15], v[86:87], v[80:81]
	v_lshlrev_b32_e32 v86, 16, v90
	v_and_b32_e32 v87, 0xffff0000, v90
	s_waitcnt vmcnt(13)
	v_pk_fma_f32 v[84:85], v[8:9], v[86:87], v[84:85]
	v_lshlrev_b32_e32 v86, 16, v91
	v_and_b32_e32 v87, 0xffff0000, v91
	v_pk_fma_f32 v[78:79], v[10:11], v[86:87], v[78:79]
	v_lshlrev_b32_e32 v86, 16, v92
	v_and_b32_e32 v87, 0xffff0000, v92
	s_waitcnt vmcnt(12)
	v_pk_fma_f32 v[82:83], v[0:1], v[86:87], v[82:83]
	v_min_f32_e64 v86, -v84, s52
	v_min_f32_e64 v87, -v85, s52
	v_mul_f32_e32 v86, 0x3fb8aa3b, v86
	v_mul_f32_e32 v87, 0x3fb8aa3b, v87
	v_exp_f32_e32 v86, v86
	v_exp_f32_e32 v87, v87
	v_lshlrev_b32_e32 v88, 16, v93
	v_and_b32_e32 v89, 0xffff0000, v93
	v_pk_fma_f32 v[80:81], v[2:3], v[88:89], v[80:81]
	v_pk_add_f32 v[86:87], v[86:87], 1.0 op_sel_hi:[1,0]
	v_min_f32_e64 v89, -v79, s52
	v_mul_f32_e32 v88, v86, v87
	v_rcp_f32_e32 v90, v88
	v_min_f32_e64 v88, -v78, s52
	v_mul_f32_e32 v88, 0x3fb8aa3b, v88
	v_mul_f32_e32 v89, 0x3fb8aa3b, v89
	v_exp_f32_e32 v88, v88
	v_exp_f32_e32 v89, v89
	v_mul_f32_e32 v87, v87, v90
	v_mul_f32_e32 v90, v86, v90
	v_mul_f32_e32 v91, v84, v87
	v_pk_add_f32 v[86:87], v[88:89], 1.0 op_sel_hi:[1,0]
	v_min_f32_e64 v88, -v82, s52
	v_min_f32_e64 v89, -v83, s52
	v_mul_f32_e32 v84, v86, v87
	v_mul_f32_e32 v88, 0x3fb8aa3b, v88
	v_mul_f32_e32 v89, 0x3fb8aa3b, v89
	v_rcp_f32_e32 v84, v84
	v_exp_f32_e32 v88, v88
	v_exp_f32_e32 v89, v89
	v_mul_f32_e32 v90, v85, v90
	v_mul_f32_e32 v92, v87, v84
	v_mul_f32_e32 v93, v86, v84
	v_pk_add_f32 v[84:85], v[88:89], 1.0 op_sel_hi:[1,0]
	v_min_f32_e64 v87, -v81, s52
	v_mul_f32_e32 v86, v84, v85
	v_rcp_f32_e32 v88, v86
	v_min_f32_e64 v86, -v80, s52
	v_mul_f32_e32 v86, 0x3fb8aa3b, v86
	v_mul_f32_e32 v87, 0x3fb8aa3b, v87
	v_exp_f32_e32 v86, v86
	v_exp_f32_e32 v87, v87
	v_mul_f32_e32 v89, v78, v92
	v_mul_f32_e32 v92, v79, v93
	v_mul_f32_e32 v84, v84, v88
	v_pk_add_f32 v[78:79], v[86:87], 1.0 op_sel_hi:[1,0]
	v_mul_f32_e32 v85, v85, v88
	v_mul_f32_e32 v86, v78, v79
	v_rcp_f32_e32 v86, v86
	v_mul_f32_e32 v83, v83, v84
	v_mul_f32_e32 v82, v82, v85
	s_waitcnt vmcnt(10)
	v_and_b32_e32 v87, 0xffff0000, v98
	v_mul_f32_e32 v79, v79, v86
	v_mul_f32_e32 v78, v78, v86
	v_mul_f32_e32 v84, v80, v79
	v_mul_f32_e32 v81, v81, v78
	v_cvt_pk_bf16_f32 v78, v91, v90
	v_cvt_pk_bf16_f32 v79, v89, v92
	v_cvt_pk_bf16_f32 v80, v82, v83
	v_cvt_pk_bf16_f32 v81, v84, v81
	ds_write_b128 v204, v[78:81]
	v_lshlrev_b32_e32 v78, 16, v94
	v_and_b32_e32 v79, 0xffff0000, v94
	v_pk_fma_f32 v[78:79], v[4:5], v[78:79], v[40:41]
	v_lshlrev_b32_e32 v80, 16, v95
	v_and_b32_e32 v81, 0xffff0000, v95
	v_lshlrev_b32_e32 v86, 16, v98
	v_pk_fma_f32 v[80:81], v[6:7], v[80:81], v[42:43]
	v_lshlrev_b32_e32 v82, 16, v96
	v_and_b32_e32 v83, 0xffff0000, v96
	v_pk_fma_f32 v[78:79], v[28:29], v[86:87], v[78:79]
	v_lshlrev_b32_e32 v86, 16, v99
	v_and_b32_e32 v87, 0xffff0000, v99
	v_pk_fma_f32 v[82:83], v[32:33], v[82:83], v[36:37]
	v_lshlrev_b32_e32 v84, 16, v97
	v_and_b32_e32 v85, 0xffff0000, v97
	v_pk_fma_f32 v[80:81], v[30:31], v[86:87], v[80:81]
	v_lshlrev_b32_e32 v86, 16, v100
	v_and_b32_e32 v87, 0xffff0000, v100
	v_pk_fma_f32 v[84:85], v[34:35], v[84:85], v[38:39]
	v_pk_fma_f32 v[82:83], v[24:25], v[86:87], v[82:83]
	v_lshlrev_b32_e32 v86, 16, v101
	v_and_b32_e32 v87, 0xffff0000, v101
	v_pk_fma_f32 v[84:85], v[26:27], v[86:87], v[84:85]
	s_waitcnt vmcnt(9)
	v_lshlrev_b32_e32 v86, 16, v102
	v_and_b32_e32 v87, 0xffff0000, v102
	v_pk_fma_f32 v[78:79], v[20:21], v[86:87], v[78:79]
	v_lshlrev_b32_e32 v86, 16, v103
	v_and_b32_e32 v87, 0xffff0000, v103
	v_pk_fma_f32 v[80:81], v[22:23], v[86:87], v[80:81]
	v_lshlrev_b32_e32 v86, 16, v104
	v_and_b32_e32 v87, 0xffff0000, v104
	v_pk_fma_f32 v[82:83], v[12:13], v[86:87], v[82:83]
	v_lshlrev_b32_e32 v86, 16, v105
	v_and_b32_e32 v87, 0xffff0000, v105
	v_pk_fma_f32 v[84:85], v[14:15], v[86:87], v[84:85]
	s_waitcnt vmcnt(8)
	v_lshlrev_b32_e32 v86, 16, v72
	v_and_b32_e32 v87, 0xffff0000, v72
	v_pk_fma_f32 v[78:79], v[8:9], v[86:87], v[78:79]
	v_lshlrev_b32_e32 v72, 16, v73
	v_and_b32_e32 v73, 0xffff0000, v73
	v_pk_fma_f32 v[72:73], v[10:11], v[72:73], v[80:81]
	v_lshlrev_b32_e32 v80, 16, v74
	v_and_b32_e32 v81, 0xffff0000, v74
	v_min_f32_e64 v74, -v78, s52
	v_mul_f32_e32 v74, 0x3fb8aa3b, v74
	v_pk_fma_f32 v[80:81], v[0:1], v[80:81], v[82:83]
	v_exp_f32_e32 v82, v74
	v_min_f32_e64 v74, -v79, s52
	v_mul_f32_e32 v74, 0x3fb8aa3b, v74
	v_exp_f32_e32 v83, v74
	v_lshlrev_b32_e32 v74, 16, v75
	v_and_b32_e32 v75, 0xffff0000, v75
	v_pk_fma_f32 v[74:75], v[2:3], v[74:75], v[84:85]
	v_pk_add_f32 v[82:83], v[82:83], 1.0 op_sel_hi:[1,0]
	v_min_f32_e64 v85, -v73, s52
	v_mul_f32_e32 v84, v82, v83
	v_rcp_f32_e32 v86, v84
	v_min_f32_e64 v84, -v72, s52
	v_mul_f32_e32 v84, 0x3fb8aa3b, v84
	v_mul_f32_e32 v85, 0x3fb8aa3b, v85
	v_exp_f32_e32 v84, v84
	v_exp_f32_e32 v85, v85
	v_mul_f32_e32 v83, v83, v86
	v_mul_f32_e32 v86, v82, v86
	v_mul_f32_e32 v87, v78, v83
	v_pk_add_f32 v[82:83], v[84:85], 1.0 op_sel_hi:[1,0]
	v_min_f32_e64 v84, -v80, s52
	v_min_f32_e64 v85, -v81, s52
	v_mul_f32_e32 v78, v82, v83
	v_mul_f32_e32 v84, 0x3fb8aa3b, v84
	v_mul_f32_e32 v85, 0x3fb8aa3b, v85
	v_rcp_f32_e32 v78, v78
	v_exp_f32_e32 v84, v84
	v_exp_f32_e32 v85, v85
	v_mul_f32_e32 v86, v79, v86
	v_mul_f32_e32 v88, v83, v78
	v_mul_f32_e32 v89, v82, v78
	v_pk_add_f32 v[78:79], v[84:85], 1.0 op_sel_hi:[1,0]
	v_min_f32_e64 v83, -v75, s52
	v_mul_f32_e32 v82, v78, v79
	v_rcp_f32_e32 v84, v82
	v_min_f32_e64 v82, -v74, s52
	v_mul_f32_e32 v82, 0x3fb8aa3b, v82
	v_mul_f32_e32 v83, 0x3fb8aa3b, v83
	v_exp_f32_e32 v82, v82
	v_exp_f32_e32 v83, v83
	v_mul_f32_e32 v85, v72, v88
	v_mul_f32_e32 v88, v73, v89
	v_mul_f32_e32 v79, v79, v84
	v_pk_add_f32 v[72:73], v[82:83], 1.0 op_sel_hi:[1,0]
	v_mul_f32_e32 v78, v78, v84
	v_mul_f32_e32 v82, v72, v73
	v_rcp_f32_e32 v82, v82
	v_mul_f32_e32 v79, v80, v79
	v_mul_f32_e32 v78, v81, v78
	v_mul_f32_e32 v73, v73, v82
	v_mul_f32_e32 v72, v72, v82
	v_mul_f32_e32 v80, v74, v73
	v_mul_f32_e32 v75, v75, v72
	v_cvt_pk_bf16_f32 v72, v87, v86
	v_cvt_pk_bf16_f32 v73, v85, v88
	v_cvt_pk_bf16_f32 v74, v79, v78
	v_cvt_pk_bf16_f32 v75, v80, v75
	ds_write_b128 v204, v[72:75] offset:4608
	s_waitcnt vmcnt(7)
; #define LAS __attribute__((address_space(3)))
; __device__ __forceinline__ float bflo(unsigned w) { return __uint_as_float(w << 16); }
; __device__ __forceinline__ float bfhi(unsigned w) { return __uint_as_float(w & 0xffff0000u); }
; __device__ __forceinline__ void conv8_math(const u32x4 (&raw)[4], const float (&w)[4][8], const float (&bias)[8], float (&o)[8]) {
;     f32x2 a[4];
; #pragma unroll
;     for (int j = 0; j < 4; ++j) a[j] = (f32x2){bias[2 * j], bias[2 * j + 1]};
; #pragma unroll
;     for (int k = 0; k < 4; ++k) {
; #pragma unroll
;         for (int j = 0; j < 4; ++j) { const unsigned u = raw[k][j]; const f32x2 v = (f32x2){bflo(u), bfhi(u)}, wv = (f32x2){w[k][2 * j], w[k][2 * j + 1]}; a[j] = wv * v + a[j]; } }
; #pragma unroll
;     for (int j = 0; j < 4; ++j) { float sa, sb; sigmoid2(a[j].x, a[j].y, sa, sb); o[2 * j] = a[j].x * sa; o[2 * j + 1] = a[j].y * sb; }
; __device__ void phase_ssd_out(KP P, int layer, LAS unsigned char* lds) {
;     ...
;             for (int i = 0; i < 4; ++i) { const int l = (tid >> 4) + 32 * i; float o[8]; conv8_math(rbc[i], w, bias, o);
;                 *(LAS u32x4*)(dstb + l * 72) = __builtin_bit_cast(u32x4, pack8(o)); }
	v_lshlrev_b32_e32 v72, 16, v68
	v_and_b32_e32 v73, 0xffff0000, v68
	v_lshlrev_b32_e32 v68, 16, v69
	v_and_b32_e32 v69, 0xffff0000, v69
	v_pk_fma_f32 v[68:69], v[6:7], v[68:69], v[42:43]
	v_lshlrev_b32_e32 v74, 16, v70
	v_and_b32_e32 v75, 0xffff0000, v70
	v_lshlrev_b32_e32 v70, 16, v71
	v_and_b32_e32 v71, 0xffff0000, v71
	s_waitcnt vmcnt(6)
	v_lshlrev_b32_e32 v78, 16, v64
	v_and_b32_e32 v79, 0xffff0000, v64
	v_lshlrev_b32_e32 v64, 16, v65
	v_and_b32_e32 v65, 0xffff0000, v65
	v_pk_fma_f32 v[70:71], v[34:35], v[70:71], v[38:39]
	v_pk_fma_f32 v[64:65], v[30:31], v[64:65], v[68:69]
	v_lshlrev_b32_e32 v68, 16, v66
	v_and_b32_e32 v69, 0xffff0000, v66
	v_lshlrev_b32_e32 v66, 16, v67
	v_and_b32_e32 v67, 0xffff0000, v67
	v_pk_fma_f32 v[72:73], v[4:5], v[72:73], v[40:41]
	v_pk_fma_f32 v[66:67], v[26:27], v[66:67], v[70:71]
	s_waitcnt vmcnt(5)
	v_lshlrev_b32_e32 v70, 16, v60
	v_and_b32_e32 v71, 0xffff0000, v60
	v_lshlrev_b32_e32 v60, 16, v61
	v_and_b32_e32 v61, 0xffff0000, v61
	v_pk_fma_f32 v[72:73], v[28:29], v[78:79], v[72:73]
	v_pk_fma_f32 v[60:61], v[22:23], v[60:61], v[64:65]
	v_lshlrev_b32_e32 v64, 16, v62
	v_and_b32_e32 v65, 0xffff0000, v62
	v_lshlrev_b32_e32 v62, 16, v63
	v_and_b32_e32 v63, 0xffff0000, v63
	v_pk_fma_f32 v[70:71], v[20:21], v[70:71], v[72:73]
	v_pk_fma_f32 v[62:63], v[14:15], v[62:63], v[66:67]
	s_waitcnt vmcnt(4)
	v_lshlrev_b32_e32 v66, 16, v56
	v_and_b32_e32 v67, 0xffff0000, v56
	v_pk_fma_f32 v[74:75], v[32:33], v[74:75], v[36:37]
	v_pk_fma_f32 v[66:67], v[8:9], v[66:67], v[70:71]
	v_lshlrev_b32_e32 v56, 16, v57
	v_and_b32_e32 v57, 0xffff0000, v57
	v_pk_fma_f32 v[68:69], v[24:25], v[68:69], v[74:75]
	v_pk_fma_f32 v[56:57], v[10:11], v[56:57], v[60:61]
	v_lshlrev_b32_e32 v60, 16, v58
	v_and_b32_e32 v61, 0xffff0000, v58
	v_min_f32_e64 v58, -v66, s52
	v_pk_fma_f32 v[64:65], v[12:13], v[64:65], v[68:69]
	v_mul_f32_e32 v58, 0x3fb8aa3b, v58
	v_pk_fma_f32 v[60:61], v[0:1], v[60:61], v[64:65]
	v_exp_f32_e32 v64, v58
	v_min_f32_e64 v58, -v67, s52
	v_mul_f32_e32 v58, 0x3fb8aa3b, v58
	v_exp_f32_e32 v65, v58
	v_lshlrev_b32_e32 v58, 16, v59
	v_and_b32_e32 v59, 0xffff0000, v59
	v_pk_fma_f32 v[58:59], v[2:3], v[58:59], v[62:63]
	v_pk_add_f32 v[62:63], v[64:65], 1.0 op_sel_hi:[1,0]
	v_min_f32_e64 v65, -v57, s52
	v_mul_f32_e32 v64, v62, v63
	v_rcp_f32_e32 v68, v64
	v_min_f32_e64 v64, -v56, s52
	v_mul_f32_e32 v64, 0x3fb8aa3b, v64
	v_mul_f32_e32 v65, 0x3fb8aa3b, v65
	v_exp_f32_e32 v64, v64
	v_exp_f32_e32 v65, v65
	v_mul_f32_e32 v63, v63, v68
	v_mul_f32_e32 v68, v62, v68
	v_mul_f32_e32 v66, v66, v63
	v_pk_add_f32 v[62:63], v[64:65], 1.0 op_sel_hi:[1,0]
	v_min_f32_e64 v65, -v61, s52
	v_mul_f32_e32 v64, v62, v63
	v_rcp_f32_e32 v69, v64
	v_min_f32_e64 v64, -v60, s52
	v_mul_f32_e32 v64, 0x3fb8aa3b, v64
	v_mul_f32_e32 v65, 0x3fb8aa3b, v65
	v_exp_f32_e32 v64, v64
	v_exp_f32_e32 v65, v65
	v_mul_f32_e32 v67, v67, v68
	v_mul_f32_e32 v68, v63, v69
	v_mul_f32_e32 v69, v62, v69
	v_pk_add_f32 v[62:63], v[64:65], 1.0 op_sel_hi:[1,0]
	v_min_f32_e64 v65, -v59, s52
	v_mul_f32_e32 v64, v62, v63
	v_rcp_f32_e32 v70, v64
	v_min_f32_e64 v64, -v58, s52
	v_mul_f32_e32 v64, 0x3fb8aa3b, v64
	v_mul_f32_e32 v65, 0x3fb8aa3b, v65
	v_exp_f32_e32 v64, v64
	v_exp_f32_e32 v65, v65
	v_mul_f32_e32 v68, v56, v68
	v_mul_f32_e32 v69, v57, v69
	v_mul_f32_e32 v62, v62, v70
	v_pk_add_f32 v[56:57], v[64:65], 1.0 op_sel_hi:[1,0]
	v_mul_f32_e32 v63, v63, v70
	v_mul_f32_e32 v64, v56, v57
	v_rcp_f32_e32 v64, v64
	v_mul_f32_e32 v61, v61, v62
	v_mul_f32_e32 v60, v60, v63
	v_mul_f32_e32 v57, v57, v64
	v_mul_f32_e32 v56, v56, v64
	v_mul_f32_e32 v62, v58, v57
	v_mul_f32_e32 v59, v59, v56
	v_cvt_pk_bf16_f32 v56, v66, v67
	v_cvt_pk_bf16_f32 v57, v68, v69
	v_cvt_pk_bf16_f32 v58, v60, v61
	v_cvt_pk_bf16_f32 v59, v62, v59
	ds_write_b128 v204, v[56:59] offset:9216
	s_waitcnt vmcnt(3)
	v_lshlrev_b32_e32 v56, 16, v52
	v_and_b32_e32 v57, 0xffff0000, v52
	v_pk_fma_f32 v[4:5], v[4:5], v[56:57], v[40:41]
	v_lshlrev_b32_e32 v40, 16, v53
	v_and_b32_e32 v41, 0xffff0000, v53
	v_pk_fma_f32 v[6:7], v[6:7], v[40:41], v[42:43]
	v_lshlrev_b32_e32 v40, 16, v54
	v_and_b32_e32 v41, 0xffff0000, v54
	v_pk_fma_f32 v[32:33], v[32:33], v[40:41], v[36:37]
	v_lshlrev_b32_e32 v36, 16, v55
	v_and_b32_e32 v37, 0xffff0000, v55
	v_pk_fma_f32 v[34:35], v[34:35], v[36:37], v[38:39]
	s_waitcnt vmcnt(2)
; #define LAS __attribute__((address_space(3)))
; __device__ void phase_ssd_out(KP P, int layer, LAS unsigned char* lds) {
;     ...
;             for (int i = 0; i < 4; ++i) { const int l = (tid >> 4) + 32 * i; float o[8]; conv8_math(rbc[i], w, bias, o);
;                 *(LAS u32x4*)(dstb + l * 72) = __builtin_bit_cast(u32x4, pack8(o)); }
;         }
;         __syncthreads();
;         const float Dh = P->d_skip[layer * 16 + h];
;         const LAS float* csw = csA + wid * 128; const LAS float* dtw = dtA + wid * 128; const LAS float* fsw = fsA + wid * 128;
;         const bf16_t* stp = states + (((size_t)bc * 16 + h) << 12);
;         bf16_t* zbase = proj + row0 * PW + COL_Z + h * 64;
;         LAS unsigned char* xdw = xdL + wid * 8192;
;         const int xsl = (lane ^ ((r >> 3) + 2 * q)) << 4;
	v_lshlrev_b32_e32 v36, 16, v48
	v_and_b32_e32 v37, 0xffff0000, v48
	v_pk_fma_f32 v[4:5], v[28:29], v[36:37], v[4:5]
	v_lshlrev_b32_e32 v28, 16, v49
	v_and_b32_e32 v29, 0xffff0000, v49
	v_pk_fma_f32 v[6:7], v[30:31], v[28:29], v[6:7]
	v_lshlrev_b32_e32 v28, 16, v50
	v_and_b32_e32 v29, 0xffff0000, v50
	v_pk_fma_f32 v[24:25], v[24:25], v[28:29], v[32:33]
	v_lshlrev_b32_e32 v28, 16, v51
	v_and_b32_e32 v29, 0xffff0000, v51
	v_pk_fma_f32 v[26:27], v[26:27], v[28:29], v[34:35]
	s_waitcnt vmcnt(1)
	v_lshlrev_b32_e32 v28, 16, v44
	v_and_b32_e32 v29, 0xffff0000, v44
	v_pk_fma_f32 v[4:5], v[20:21], v[28:29], v[4:5]
	v_lshlrev_b32_e32 v20, 16, v45
	v_and_b32_e32 v21, 0xffff0000, v45
	v_pk_fma_f32 v[6:7], v[22:23], v[20:21], v[6:7]
	v_lshlrev_b32_e32 v20, 16, v46
	v_and_b32_e32 v21, 0xffff0000, v46
	v_pk_fma_f32 v[12:13], v[12:13], v[20:21], v[24:25]
	v_lshlrev_b32_e32 v20, 16, v47
	v_and_b32_e32 v21, 0xffff0000, v47
	v_pk_fma_f32 v[14:15], v[14:15], v[20:21], v[26:27]
	s_waitcnt vmcnt(0)
	v_lshlrev_b32_e32 v20, 16, v16
	v_and_b32_e32 v21, 0xffff0000, v16
	v_pk_fma_f32 v[4:5], v[8:9], v[20:21], v[4:5]
	v_lshlrev_b32_e32 v8, 16, v17
	v_and_b32_e32 v9, 0xffff0000, v17
	v_pk_fma_f32 v[6:7], v[10:11], v[8:9], v[6:7]
	v_lshlrev_b32_e32 v8, 16, v18
	v_and_b32_e32 v9, 0xffff0000, v18
	v_pk_fma_f32 v[0:1], v[0:1], v[8:9], v[12:13]
	v_min_f32_e64 v8, -v4, s52
	v_min_f32_e64 v9, -v5, s52
	v_mul_f32_e32 v8, 0x3fb8aa3b, v8
	v_mul_f32_e32 v9, 0x3fb8aa3b, v9
	v_exp_f32_e32 v8, v8
	v_exp_f32_e32 v9, v9
	v_lshlrev_b32_e32 v10, 16, v19
	v_and_b32_e32 v11, 0xffff0000, v19
	v_pk_fma_f32 v[2:3], v[2:3], v[10:11], v[14:15]
	v_pk_add_f32 v[8:9], v[8:9], 1.0 op_sel_hi:[1,0]
	v_min_f32_e64 v11, -v7, s52
	v_mul_f32_e32 v10, v8, v9
	v_rcp_f32_e32 v12, v10
	v_min_f32_e64 v10, -v6, s52
	v_mul_f32_e32 v10, 0x3fb8aa3b, v10
	v_mul_f32_e32 v11, 0x3fb8aa3b, v11
	v_exp_f32_e32 v10, v10
	v_exp_f32_e32 v11, v11
	v_mul_f32_e32 v9, v9, v12
	v_mul_f32_e32 v12, v8, v12
	v_mul_f32_e32 v13, v4, v9
	v_pk_add_f32 v[8:9], v[10:11], 1.0 op_sel_hi:[1,0]
	v_min_f32_e64 v10, -v0, s52
	v_min_f32_e64 v11, -v1, s52
	v_mul_f32_e32 v4, v8, v9
	v_mul_f32_e32 v10, 0x3fb8aa3b, v10
	v_mul_f32_e32 v11, 0x3fb8aa3b, v11
	v_rcp_f32_e32 v4, v4
	v_exp_f32_e32 v10, v10
	v_exp_f32_e32 v11, v11
	v_mul_f32_e32 v12, v5, v12
	v_mul_f32_e32 v14, v9, v4
	v_mul_f32_e32 v15, v8, v4
	v_pk_add_f32 v[4:5], v[10:11], 1.0 op_sel_hi:[1,0]
	v_min_f32_e64 v9, -v3, s52
	v_mul_f32_e32 v8, v4, v5
	v_rcp_f32_e32 v10, v8
	v_min_f32_e64 v8, -v2, s52
	v_mul_f32_e32 v8, 0x3fb8aa3b, v8
	v_mul_f32_e32 v9, 0x3fb8aa3b, v9
	v_exp_f32_e32 v8, v8
	v_exp_f32_e32 v9, v9
	v_mul_f32_e32 v11, v6, v14
	v_mul_f32_e32 v14, v7, v15
	v_mul_f32_e32 v4, v4, v10
	v_pk_add_f32 v[6:7], v[8:9], 1.0 op_sel_hi:[1,0]
	v_mul_f32_e32 v5, v5, v10
	v_mul_f32_e32 v8, v6, v7
	v_rcp_f32_e32 v8, v8
	v_mul_f32_e32 v4, v1, v4
	v_mul_f32_e32 v5, v0, v5
	v_mul_f32_e32 v1, v6, v8
	v_mul_f32_e32 v0, v7, v8
	v_mul_f32_e32 v3, v3, v1
	v_mul_f32_e32 v6, v2, v0
	v_cvt_pk_bf16_f32 v0, v13, v12
	v_cvt_pk_bf16_f32 v1, v11, v14
	v_cvt_pk_bf16_f32 v2, v5, v4
	v_cvt_pk_bf16_f32 v3, v6, v3
	ds_write_b128 v204, v[0:3] offset:13824
	s_waitcnt lgkmcnt(0)
	s_barrier
	s_load_dwordx2 s[24:25], s[36:37], 0x48
	v_add_u32_e32 v0, s19, v76
	v_ashrrev_i32_e32 v1, 31, v0
	v_or_b32_e32 v2, s14, v191
	v_mad_u32_u24 v179, v2, s55, v217
	s_waitcnt lgkmcnt(0)
	v_lshl_add_u64 v[0:1], v[0:1], 2, s[24:25]
	global_load_dword v167, v[0:1], off
	v_lshlrev_b64 v[0:1], 13, v[76:77]
	v_lshl_add_u64 v[0:1], s[10:11], 0, v[0:1]
	s_mul_i32 s10, s13, 0x2200
	s_mul_hi_u32 s11, s12, 0x2200
	s_add_i32 s11, s11, s10
	s_mulk_i32 s12, 0x2200
	s_add_u32 s10, s3, s12
	s_addc_u32 s11, s16, s11
	v_lshl_add_u64 v[182:183], v[180:181], 1, s[10:11]
	v_lshl_add_u64 v[184:185], v[0:1], 0, v[160:161]
	v_lshl_add_u64 v[0:1], v[182:183], 0, v[162:163]
	v_lshl_add_u64 v[186:187], v[0:1], 0, v[164:165]
	v_mov_b32_e32 v0, 0x11000
	v_mad_u32_u24 v163, v2, s55, v0
	v_mov_b32_e32 v0, 0x22000
	v_mad_u32_u24 v165, v2, s55, v0
	v_mov_b32_e32 v0, 0x33000
	v_mad_u32_u24 v177, v2, s55, v0
	v_mov_b32_e32 v0, 0x77000
	v_mul_u32_u24_e32 v161, 0x1100, v2
	v_mad_u32_u24 v230, v2, s55, v218
	v_mad_u32_u24 v231, v2, s55, v219
	v_mad_u32_u24 v232, v2, s55, v0
	s_mov_b64 s[12:13], -1
	s_branch .LBB0_26

; __device__ __forceinline__ float softplus_f(float v) { return v > 20.f ? v : log1pf(__expf(v)); }
; __device__ __forceinline__ void dt_cumsum(const float* dtb, long row0, int h, float bias, float A, int lane, float& d0, float& d1, float& cs0, float& cs1, float& tot) {
;     d0 = softplus_f(dtb[(row0 + 2 * lane) * 16 + h] + bias); d1 = softplus_f(dtb[(row0 + 2 * lane + 1) * 16 + h] + bias);
; __device__ void phase_states(KP P, int layer, LAS unsigned char* lds) {
;     ...
;     for (int item = blockIdx.x; item < 512; item += nblk) {
;         const int g = item & 1, bc = item >> 1, b = bc >> 6, c = bc & 63, tbase = c * 128, h = g * 8 + wid;
;         const long row0 = (long)b * SEQ + tbase;
;         const __amdgpu_buffer_rsrc_t rsq = seq_rsrc(proj, row0, tbase);
;         u32x4 rbb[2][4];
; #pragma unroll
;         for (int i = 0; i < 2; ++i) conv8_load(rsq, tbase, (tid >> 3) + 64 * i, 1024 + g * 64 + (tid & 7) * 8, rbb[i]);
;         { float d0, d1, cs0, cs1, tot; dt_cumsum(dtb, row0, h, P->dt_bias[layer * 16 + h], -expf(P->a_log[layer * 16 + h]), lane, d0, d1, cs0, cs1, tot);
.LBB0_73:
	s_ashr_i32 s12, s20, 1
	s_ashr_i32 s14, s20, 7
	s_lshl_b32 s13, s12, 7
	s_and_b32 s23, s20, 1
	s_and_b32 s13, s13, 0x1f80
	s_ashr_i32 s15, s14, 31
	s_mul_i32 s24, s14, 0x4400000
	s_mul_hi_i32 s22, s14, 0x4400000
	s_add_u32 s64, s3, s24
	v_lshl_add_u32 v180, s23, 3, v175
	s_addc_u32 s22, s16, s22
	v_add_u32_e32 v32, s19, v180
	s_and_b32 s65, s22, 0xffff
	s_lshl_b32 s22, s23, 6
	v_add_u32_e32 v0, s13, v182
	v_ashrrev_i32_e32 v33, 31, v32
	v_or_b32_e32 v1, s22, v230
	v_mul_lo_u32 v0, v0, s55
	s_lshl_b64 s[14:15], s[14:15], 13
	v_lshlrev_b64 v[32:33], 2, v[32:33]
	v_add_lshl_u32 v0, v0, v1, 1
	s_or_b32 s14, s14, s13
	v_lshl_add_u64 v[34:35], s[60:61], 0, v[32:33]
	v_lshl_add_u64 v[32:33], s[62:63], 0, v[32:33]
	global_load_dword v38, v[34:35], off
	global_load_dword v34, v[32:33], off
	v_mov_b32_e32 v33, s15
	v_or_b32_e32 v32, s14, v174
	v_lshlrev_b64 v[36:37], 6, v[32:33]
	v_ashrrev_i32_e32 v181, 31, v180
	v_lshl_add_u64 v[36:37], s[4:5], 0, v[36:37]
	v_lshl_add_u64 v[36:37], v[180:181], 2, v[36:37]
	global_load_dword v35, v[36:37], off
	global_load_dword v36, v[36:37], off offset:64
	v_add_u32_e32 v1, 0x2000, v0
	buffer_load_dwordx4 v[24:27], v1, s[64:67], 0 offen offset:512
	v_add_u32_e32 v1, 0x4000, v0
	buffer_load_dwordx4 v[20:23], v1, s[64:67], 0 offen offset:1024
	v_add_u32_e32 v1, 0x6000, v0
	buffer_load_dwordx4 v[16:19], v1, s[64:67], 0 offen offset:1536
	v_add_u32_e32 v1, 0x88000, v0
	buffer_load_dwordx4 v[28:31], v0, s[64:67], 0 offen
	buffer_load_dwordx4 v[12:15], v1, s[64:67], 0 offen
	v_add_u32_e32 v1, 0x8a000, v0
	buffer_load_dwordx4 v[8:11], v1, s[64:67], 0 offen offset:512
	v_add_u32_e32 v1, 0x8c000, v0
	v_add_u32_e32 v0, 0x8e000, v0
	buffer_load_dwordx4 v[4:7], v1, s[64:67], 0 offen offset:1024
	buffer_load_dwordx4 v[0:3], v0, s[64:67], 0 offen offset:1536
	s_waitcnt vmcnt(8)
	v_add_f32_e32 v35, v38, v35
	v_cmp_nlt_f32_e32 vcc, s26, v35
	s_and_saveexec_b64 s[14:15], vcc
	s_cbranch_execz .LBB0_75
	v_mul_f32_e32 v35, 0x3fb8aa3b, v35
	v_exp_f32_e32 v35, v35
	s_nop 0
	v_add_f32_e32 v39, 1.0, v35
	v_frexp_mant_f32_e32 v43, v39
	v_cvt_f64_f32_e32 v[40:41], v39
	v_add_f32_e32 v42, -1.0, v39
	v_frexp_exp_i32_f64_e32 v40, v[40:41]
	v_cmp_gt_f32_e32 vcc, s27, v43
	v_sub_f32_e32 v44, v42, v39
	v_sub_f32_e32 v42, v35, v42
	v_subbrev_co_u32_e32 v48, vcc, 0, v40, vcc
	v_add_f32_e32 v44, 1.0, v44
	v_sub_u32_e32 v40, 0, v48
	v_add_f32_e32 v42, v42, v44
	v_ldexp_f32 v39, v39, v40
	v_ldexp_f32 v40, v42, v40
	v_add_f32_e32 v42, -1.0, v39
	v_add_f32_e32 v41, 1.0, v42
	v_sub_f32_e32 v41, v39, v41
	v_add_f32_e32 v43, v40, v41
	v_add_f32_e32 v41, 1.0, v39
	v_add_f32_e32 v44, -1.0, v41
	v_sub_f32_e32 v39, v39, v44
	v_add_f32_e32 v39, v40, v39
	v_add_f32_e32 v49, v41, v39
	v_rcp_f32_e32 v50, v49
	v_sub_f32_e32 v40, v49, v41
	v_add_f32_e32 v41, v42, v43
	v_sub_f32_e32 v39, v39, v40
	v_mul_f32_e32 v52, v41, v50
	v_sub_f32_e32 v40, v41, v42
	v_mul_f32_e32 v42, v49, v52
	v_fma_f32 v44, v52, v49, -v42
	v_fmac_f32_e32 v44, v52, v39
	v_sub_f32_e32 v51, v43, v40
	v_add_f32_e32 v40, v42, v44
	v_sub_f32_e32 v43, v41, v40
	v_pk_add_f32 v[46:47], v[40:41], v[42:43] neg_lo:[0,1] neg_hi:[0,1]
	v_mov_b32_e32 v45, v40
	v_pk_add_f32 v[40:41], v[46:47], v[44:45] neg_lo:[0,1] neg_hi:[0,1]
	v_cmp_neq_f32_e32 vcc, s29, v35
	v_add_f32_e32 v41, v51, v41
	v_add_f32_e32 v40, v40, v41
	v_add_f32_e32 v41, v43, v40
	v_mul_f32_e32 v51, v50, v41
	v_mul_f32_e32 v42, v49, v51
	v_fma_f32 v44, v51, v49, -v42
	v_fmac_f32_e32 v44, v51, v39
	v_sub_f32_e32 v39, v43, v41
	v_add_f32_e32 v39, v40, v39
	v_add_f32_e32 v40, v42, v44
	v_sub_f32_e32 v43, v41, v40
	v_pk_add_f32 v[46:47], v[40:41], v[42:43] neg_lo:[0,1] neg_hi:[0,1]
	v_mov_b32_e32 v45, v40
	v_pk_add_f32 v[40:41], v[46:47], v[44:45] neg_lo:[0,1] neg_hi:[0,1]
	s_nop 0
	v_add_f32_e32 v39, v39, v41
	v_add_f32_e32 v39, v40, v39
	v_add_f32_e32 v41, v52, v51
	v_add_f32_e32 v39, v43, v39
	v_sub_f32_e32 v40, v41, v52
	v_mul_f32_e32 v39, v50, v39
	v_sub_f32_e32 v40, v51, v40
	v_add_f32_e32 v39, v40, v39
	v_add_f32_e32 v42, v41, v39
	v_mul_f32_e32 v44, v42, v42
	v_fmamk_f32 v40, v44, 0x3e9b6dac, v210
	v_fmaak_f32 v171, v44, v40, 0x3f2aaada
	v_cvt_f32_i32_e32 v40, v48
	v_sub_f32_e32 v41, v42, v41
	v_sub_f32_e32 v39, v39, v41
	v_mul_f32_e32 v41, v42, v44
	v_pk_mul_f32 v[44:45], v[40:41], v[170:171]
	v_ldexp_f32 v43, v42, 1
	v_fma_f32 v42, v40, s28, -v44
	v_fmac_f32_e32 v42, 0xb102e308, v40
	v_pk_add_f32 v[40:41], v[44:45], v[42:43]
	v_ldexp_f32 v39, v39, 1
	v_sub_f32_e32 v43, v41, v43
	v_sub_f32_e32 v43, v45, v43
	v_add_f32_e32 v47, v39, v43
	v_mov_b32_e32 v46, v44
	v_pk_add_f32 v[44:45], v[40:41], v[44:45] neg_lo:[0,1] neg_hi:[0,1]
	v_pk_add_f32 v[48:49], v[40:41], v[46:47]
	v_mov_b32_e32 v43, v40
	v_mov_b32_e32 v45, v49
	v_pk_add_f32 v[50:51], v[42:43], v[44:45] neg_lo:[0,1] neg_hi:[0,1]
	v_pk_add_f32 v[42:43], v[42:43], v[44:45]
	v_mov_b32_e32 v46, v47
	v_pk_add_f32 v[44:45], v[42:43], v[40:41] op_sel:[1,0] op_sel_hi:[0,1] neg_lo:[0,1] neg_hi:[0,1]
	v_pk_add_f32 v[52:53], v[48:49], v[44:45] op_sel_hi:[1,0] neg_lo:[0,1] neg_hi:[0,1]
	v_mov_b32_e32 v48, v49
	v_mov_b32_e32 v49, v43
	v_pk_mov_b32 v[44:45], v[40:41], v[44:45] op_sel:[1,0]
	v_mov_b32_e32 v47, v40
	v_pk_add_f32 v[44:45], v[48:49], v[44:45] neg_lo:[0,1] neg_hi:[0,1]
	v_mov_b32_e32 v52, v50
	v_pk_add_f32 v[40:41], v[46:47], v[44:45] neg_lo:[0,1] neg_hi:[0,1]
	v_mov_b32_e32 v51, v43
	v_pk_add_f32 v[44:45], v[52:53], v[40:41]
	s_nop 0
	v_pk_add_f32 v[46:47], v[44:45], v[44:45] op_sel:[0,1] op_sel_hi:[1,0]
	s_nop 0
	v_pk_add_f32 v[42:43], v[42:43], v[46:47] op_sel:[1,0] op_sel_hi:[0,1]
	v_mov_b32_e32 v45, v42
	v_pk_add_f32 v[48:49], v[44:45], v[50:51] neg_lo:[0,1] neg_hi:[0,1]
	v_mov_b32_e32 v41, v46
	v_sub_f32_e32 v39, v44, v48
	v_pk_add_f32 v[40:41], v[40:41], v[48:49] neg_lo:[0,1] neg_hi:[0,1]
	v_sub_f32_e32 v39, v50, v39
	v_add_f32_e32 v39, v40, v39
	v_add_f32_e32 v39, v39, v41
	v_add_f32_e32 v39, v42, v39
	v_cndmask_b32_e32 v39, v221, v39, vcc
	v_cmp_ngt_f32_e32 vcc, -1.0, v35
	s_nop 1
	v_cndmask_b32_e32 v39, v222, v39, vcc
	v_cmp_neq_f32_e32 vcc, -1.0, v35
	s_nop 1
	v_cndmask_b32_e32 v39, v223, v39, vcc
	v_cmp_lt_f32_e64 vcc, |v35|, s30
	s_nop 1
	v_cndmask_b32_e32 v35, v39, v35, vcc
; __device__ __forceinline__ float softplus_f(float v) { return v > 20.f ? v : log1pf(__expf(v)); }
; __device__ __forceinline__ void dt_cumsum(const float* dtb, long row0, int h, float bias, float A, int lane, float& d0, float& d1, float& cs0, float& cs1, float& tot) {
;     d0 = softplus_f(dtb[(row0 + 2 * lane) * 16 + h] + bias); d1 = softplus_f(dtb[(row0 + 2 * lane + 1) * 16 + h] + bias);
.LBB0_75:
	s_or_b64 exec, exec, s[14:15]
	s_waitcnt vmcnt(0)
	v_add_f32_e32 v36, v38, v36
	v_cmp_nlt_f32_e32 vcc, s26, v36
	s_and_saveexec_b64 s[14:15], vcc
	s_cbranch_execz .LBB0_77
	v_mul_f32_e32 v36, 0x3fb8aa3b, v36
	v_exp_f32_e32 v50, v36
	s_nop 0
	v_add_f32_e32 v38, 1.0, v50
	v_frexp_mant_f32_e32 v40, v38
	v_cvt_f64_f32_e32 v[36:37], v38
	v_frexp_exp_i32_f64_e32 v36, v[36:37]
	v_cmp_gt_f32_e32 vcc, s27, v40
	v_add_f32_e32 v39, -1.0, v38
	v_sub_f32_e32 v41, v39, v38
	v_subbrev_co_u32_e32 v44, vcc, 0, v36, vcc
	v_sub_u32_e32 v36, 0, v44
	v_sub_f32_e32 v39, v50, v39
	v_add_f32_e32 v41, 1.0, v41
	v_ldexp_f32 v37, v38, v36
	v_add_f32_e32 v39, v39, v41
	v_add_f32_e32 v38, -1.0, v37
	v_add_f32_e32 v40, 1.0, v37
	v_ldexp_f32 v36, v39, v36
	v_add_f32_e32 v39, 1.0, v38
	v_add_f32_e32 v41, -1.0, v40
	v_sub_f32_e32 v39, v37, v39
	v_sub_f32_e32 v37, v37, v41
	v_add_f32_e32 v39, v36, v39
	v_add_f32_e32 v36, v36, v37
	v_add_f32_e32 v45, v40, v36
	v_rcp_f32_e32 v47, v45
	v_sub_f32_e32 v37, v45, v40
	v_sub_f32_e32 v46, v36, v37
	v_add_f32_e32 v37, v38, v39
	v_mul_f32_e32 v49, v37, v47
	v_sub_f32_e32 v36, v37, v38
	v_mul_f32_e32 v38, v45, v49
	v_fma_f32 v40, v49, v45, -v38
	v_fmac_f32_e32 v40, v49, v46
	v_sub_f32_e32 v48, v39, v36
	v_add_f32_e32 v36, v38, v40
	v_sub_f32_e32 v39, v37, v36
	v_pk_add_f32 v[42:43], v[36:37], v[38:39] neg_lo:[0,1] neg_hi:[0,1]
	v_mov_b32_e32 v41, v36
	v_pk_add_f32 v[36:37], v[42:43], v[40:41] neg_lo:[0,1] neg_hi:[0,1]
	v_cmp_neq_f32_e32 vcc, s29, v50
	v_add_f32_e32 v37, v48, v37
	v_add_f32_e32 v36, v36, v37
	v_add_f32_e32 v37, v39, v36
	v_mul_f32_e32 v48, v47, v37
	v_mul_f32_e32 v38, v45, v48
	v_fma_f32 v40, v48, v45, -v38
	v_fmac_f32_e32 v40, v48, v46
	v_sub_f32_e32 v39, v39, v37
	v_add_f32_e32 v45, v36, v39
	v_add_f32_e32 v36, v38, v40
	v_sub_f32_e32 v39, v37, v36
	v_pk_add_f32 v[42:43], v[36:37], v[38:39] neg_lo:[0,1] neg_hi:[0,1]
	v_mov_b32_e32 v41, v36
	v_pk_add_f32 v[36:37], v[42:43], v[40:41] neg_lo:[0,1] neg_hi:[0,1]
	s_nop 0
	v_add_f32_e32 v37, v45, v37
	v_add_f32_e32 v36, v36, v37
	v_add_f32_e32 v37, v49, v48
	v_add_f32_e32 v36, v39, v36
	v_sub_f32_e32 v38, v37, v49
	v_mul_f32_e32 v36, v47, v36
	v_sub_f32_e32 v38, v48, v38
	v_add_f32_e32 v38, v38, v36
	v_add_f32_e32 v40, v37, v38
	v_mul_f32_e32 v41, v40, v40
	v_fmamk_f32 v36, v41, 0x3e9b6dac, v210
	v_fmaak_f32 v171, v41, v36, 0x3f2aaada
	v_cvt_f32_i32_e32 v36, v44
	v_sub_f32_e32 v37, v40, v37
	v_sub_f32_e32 v37, v38, v37
	v_ldexp_f32 v42, v37, 1
	v_mul_f32_e32 v37, v40, v41
	v_ldexp_f32 v39, v40, 1
	v_pk_mul_f32 v[40:41], v[36:37], v[170:171]
	s_nop 0
	v_fma_f32 v38, v36, s28, -v40
	v_fmac_f32_e32 v38, 0xb102e308, v36
	v_pk_add_f32 v[36:37], v[40:41], v[38:39]
	s_nop 0
	v_sub_f32_e32 v39, v37, v39
	v_sub_f32_e32 v39, v41, v39
	v_add_f32_e32 v43, v42, v39
	v_mov_b32_e32 v42, v40
	v_pk_add_f32 v[40:41], v[36:37], v[40:41] neg_lo:[0,1] neg_hi:[0,1]
	v_pk_add_f32 v[44:45], v[36:37], v[42:43]
	v_mov_b32_e32 v39, v36
	v_mov_b32_e32 v41, v45
	v_pk_add_f32 v[46:47], v[38:39], v[40:41] neg_lo:[0,1] neg_hi:[0,1]
	v_pk_add_f32 v[38:39], v[38:39], v[40:41]
	v_mov_b32_e32 v42, v43
	v_pk_add_f32 v[40:41], v[38:39], v[36:37] op_sel:[1,0] op_sel_hi:[0,1] neg_lo:[0,1] neg_hi:[0,1]
	v_pk_add_f32 v[48:49], v[44:45], v[40:41] op_sel_hi:[1,0] neg_lo:[0,1] neg_hi:[0,1]
	v_mov_b32_e32 v44, v45
	v_mov_b32_e32 v45, v39
	v_pk_mov_b32 v[40:41], v[36:37], v[40:41] op_sel:[1,0]
	v_mov_b32_e32 v43, v36
	v_pk_add_f32 v[40:41], v[44:45], v[40:41] neg_lo:[0,1] neg_hi:[0,1]
	v_mov_b32_e32 v48, v46
	v_pk_add_f32 v[36:37], v[42:43], v[40:41] neg_lo:[0,1] neg_hi:[0,1]
	v_mov_b32_e32 v47, v39
	v_pk_add_f32 v[40:41], v[48:49], v[36:37]
	s_nop 0
	v_pk_add_f32 v[42:43], v[40:41], v[40:41] op_sel:[0,1] op_sel_hi:[1,0]
	s_nop 0
	v_pk_add_f32 v[38:39], v[38:39], v[42:43] op_sel:[1,0] op_sel_hi:[0,1]
	v_mov_b32_e32 v41, v38
	v_pk_add_f32 v[44:45], v[40:41], v[46:47] neg_lo:[0,1] neg_hi:[0,1]
	v_mov_b32_e32 v37, v42
	v_sub_f32_e32 v39, v40, v44
	v_pk_add_f32 v[36:37], v[36:37], v[44:45] neg_lo:[0,1] neg_hi:[0,1]
	v_sub_f32_e32 v39, v46, v39
	v_add_f32_e32 v36, v36, v39
	v_add_f32_e32 v36, v36, v37
	v_add_f32_e32 v36, v38, v36
	v_cndmask_b32_e32 v36, v221, v36, vcc
	v_cmp_ngt_f32_e32 vcc, -1.0, v50
	s_nop 1
	v_cndmask_b32_e32 v36, v222, v36, vcc
	v_cmp_neq_f32_e32 vcc, -1.0, v50
	s_nop 1
	v_cndmask_b32_e32 v36, v223, v36, vcc
	v_cmp_lt_f32_e64 vcc, |v50|, s30
	s_nop 1
	v_cndmask_b32_e32 v36, v36, v50, vcc

; __device__ __forceinline__ void transpose_tile_wave(const float* src, int ld, int k0, int c0, int valid, const float* rs, bf16_t* dst, int ldd, int j0, int lane) {
;     ...
;         if (rs) {
; #pragma unroll
;             for (int i = 0; i < 64; ++i) v[i] *= rs[k0 + i]; }
.LBB0_524:
	v_lshlrev_b32_e32 v40, 10, v74
	v_ashrrev_i32_e32 v41, 31, v40
	v_lshl_add_u64 v[40:41], v[40:41], 2, s[18:19]
	v_lshlrev_b32_e32 v168, 2, v76
	v_lshl_add_u64 v[40:41], v[40:41], 0, v[168:169]
	global_load_dwordx4 v[84:87], v[40:41], off
	global_load_dwordx4 v[88:91], v[40:41], off offset:16
	global_load_dwordx4 v[92:95], v[40:41], off offset:32
	global_load_dwordx4 v[96:99], v[40:41], off offset:48
	global_load_dwordx4 v[100:103], v[40:41], off offset:64
	global_load_dwordx4 v[104:107], v[40:41], off offset:80
	global_load_dwordx4 v[108:111], v[40:41], off offset:96
	global_load_dwordx4 v[112:115], v[40:41], off offset:112
	global_load_dwordx4 v[116:119], v[40:41], off offset:128
	global_load_dwordx4 v[120:123], v[40:41], off offset:144
	global_load_dwordx4 v[124:127], v[40:41], off offset:160
	global_load_dwordx4 v[128:131], v[40:41], off offset:176
	global_load_dwordx4 v[132:135], v[40:41], off offset:192
	global_load_dwordx4 v[136:139], v[40:41], off offset:208
	global_load_dwordx4 v[140:143], v[40:41], off offset:224
	global_load_dwordx4 v[144:147], v[40:41], off offset:240
	s_waitcnt vmcnt(0)
	v_pk_mul_f32 v[0:1], v[0:1], v[84:85]
	v_pk_mul_f32 v[2:3], v[2:3], v[86:87]
	v_pk_mul_f32 v[10:11], v[10:11], v[88:89]
	v_pk_mul_f32 v[12:13], v[12:13], v[90:91]
	v_pk_mul_f32 v[14:15], v[14:15], v[92:93]
	v_pk_mul_f32 v[16:17], v[16:17], v[94:95]
	v_pk_mul_f32 v[18:19], v[18:19], v[96:97]
	v_pk_mul_f32 v[20:21], v[20:21], v[98:99]
	v_pk_mul_f32 v[22:23], v[22:23], v[100:101]
	v_pk_mul_f32 v[24:25], v[24:25], v[102:103]
	v_pk_mul_f32 v[26:27], v[26:27], v[104:105]
	v_pk_mul_f32 v[28:29], v[28:29], v[106:107]
	v_pk_mul_f32 v[30:31], v[30:31], v[108:109]
	v_pk_mul_f32 v[32:33], v[32:33], v[110:111]
	v_pk_mul_f32 v[34:35], v[34:35], v[112:113]
	v_pk_mul_f32 v[36:37], v[36:37], v[114:115]
	v_pk_mul_f32 v[38:39], v[38:39], v[116:117]
	v_pk_mul_f32 v[42:43], v[42:43], v[118:119]
	v_pk_mul_f32 v[44:45], v[44:45], v[120:121]
	v_pk_mul_f32 v[46:47], v[46:47], v[122:123]
	v_pk_mul_f32 v[48:49], v[48:49], v[124:125]
	v_pk_mul_f32 v[50:51], v[50:51], v[126:127]
	v_pk_mul_f32 v[52:53], v[52:53], v[128:129]
	v_pk_mul_f32 v[54:55], v[54:55], v[130:131]
	v_pk_mul_f32 v[56:57], v[56:57], v[132:133]
	v_pk_mul_f32 v[58:59], v[58:59], v[134:135]
	v_pk_mul_f32 v[60:61], v[60:61], v[136:137]
	v_pk_mul_f32 v[62:63], v[62:63], v[138:139]
	v_pk_mul_f32 v[64:65], v[64:65], v[140:141]
	v_pk_mul_f32 v[66:67], v[66:67], v[142:143]
	v_pk_mul_f32 v[68:69], v[68:69], v[144:145]
	v_pk_mul_f32 v[70:71], v[70:71], v[146:147]
	s_branch .LBB0_360
